# NSA selected-block loop: hand-scheduled fast path for unmasked tiles, head-b QK MFMAs and head-a PV MFMAs interleaved with the other head's softmax VALU
# speedup vs baseline: 1.0030x; 1.0030x over previous
.LBB0_812:
	v_lshl_add_u64 v[144:145], s[62:63], 1, v[212:213]
	global_load_dwordx4 v[156:159], v[144:145], off
	global_load_dwordx4 v[152:155], v[144:145], off offset:1024
	global_load_dwordx4 v[148:151], v[144:145], off offset:2048
	s_nop 0
	global_load_dwordx4 v[144:147], v[144:145], off offset:3072
	s_add_i32 s13, s21, 31
	s_cmp_le_i32 s13, s91
	s_cbranch_scc0 .Lsel_oldp
	s_cmp_lg_u64 s[14:15], 0
	s_cbranch_scc0 .Lsel_fast
.Lsel_oldp:
	s_waitcnt vmcnt(7)
	v_mfma_f32_32x32x16_bf16 v[80:95], v[128:131], v[96:99], 0
	s_andn2_b64 vcc, exec, s[16:17]
	v_mfma_f32_32x32x16_bf16 v[64:79], v[128:131], v[112:115], 0
	s_waitcnt vmcnt(6)
	v_mfma_f32_32x32x16_bf16 v[80:95], v[132:135], v[100:103], v[80:95]
	v_mfma_f32_32x32x16_bf16 v[64:79], v[132:135], v[116:119], v[64:79]
	s_waitcnt vmcnt(5)
	v_mfma_f32_32x32x16_bf16 v[80:95], v[136:139], v[104:107], v[80:95]
	v_mfma_f32_32x32x16_bf16 v[64:79], v[136:139], v[120:123], v[64:79]
	s_waitcnt vmcnt(4)
	v_mfma_f32_32x32x16_bf16 v[80:95], v[140:143], v[108:111], v[80:95]
	v_mfma_f32_32x32x16_bf16 v[64:79], v[140:143], v[124:127], v[64:79]
	s_cbranch_vccnz .LBB0_814
	s_ashr_i32 s13, s12, 31
	v_lshl_add_u64 v[140:141], s[12:13], 1, v[210:211]
	global_load_dwordx4 v[128:131], v[140:141], off
	global_load_dwordx4 v[132:135], v[140:141], off offset:1024
	global_load_dwordx4 v[136:139], v[140:141], off offset:2048
	s_nop 0
	global_load_dwordx4 v[140:143], v[140:141], off offset:3072

.Lsel_fast:
	s_waitcnt vmcnt(7)
	v_mfma_f32_32x32x16_bf16 v[80:95], v[128:131], v[96:99], 0
	s_lshr_b32 s13, s21, 6
	s_waitcnt vmcnt(6)
	v_mfma_f32_32x32x16_bf16 v[80:95], v[132:135], v[100:103], v[80:95]
	s_lshl_b64 s[16:17], 1, s13
	s_waitcnt vmcnt(5)
	v_mfma_f32_32x32x16_bf16 v[80:95], v[136:139], v[104:107], v[80:95]
	s_waitcnt vmcnt(4)
	v_mfma_f32_32x32x16_bf16 v[80:95], v[140:143], v[108:111], v[80:95]
	v_mfma_f32_32x32x16_bf16 v[64:79], v[128:131], v[112:115], 0
	v_and_b32_e32 v217, s17, v163
	v_and_b32_e32 v216, s16, v162
	v_cmp_ne_u64_e32 vcc, 0, v[216:217]
	s_nop 8
	v_exp_f32_e32 v80, v80
	v_exp_f32_e32 v81, v81
	v_exp_f32_e32 v82, v82
	v_exp_f32_e32 v83, v83
	v_mfma_f32_32x32x16_bf16 v[64:79], v[132:135], v[116:119], v[64:79]
	v_exp_f32_e32 v84, v84
	v_exp_f32_e32 v85, v85
	v_exp_f32_e32 v86, v86
	v_exp_f32_e32 v87, v87
	v_mfma_f32_32x32x16_bf16 v[64:79], v[136:139], v[120:123], v[64:79]
	v_pk_add_f32 v[218:219], v[80:81], 0 op_sel_hi:[1,0]
	v_pk_add_f32 v[218:219], v[82:83], v[218:219]
	v_cvt_pk_bf16_f32 v80, v80, v81
	v_cvt_pk_bf16_f32 v81, v82, v83
	v_cvt_pk_bf16_f32 v82, v84, v85
	v_cvt_pk_bf16_f32 v83, v86, v87
	v_pk_add_f32 v[218:219], v[84:85], v[218:219]
	v_pk_add_f32 v[218:219], v[86:87], v[218:219]
	v_mfma_f32_32x32x16_bf16 v[64:79], v[140:143], v[124:127], v[64:79]
	v_cndmask_b32_e32 v83, 0, v83, vcc
	v_cndmask_b32_e32 v82, 0, v82, vcc
	v_cndmask_b32_e32 v81, 0, v81, vcc
	v_cndmask_b32_e32 v80, 0, v80, vcc
	s_ashr_i32 s13, s12, 31
	v_lshl_add_u64 v[140:141], s[12:13], 1, v[210:211]
	global_load_dwordx4 v[128:131], v[140:141], off
	global_load_dwordx4 v[132:135], v[140:141], off offset:1024
	global_load_dwordx4 v[136:139], v[140:141], off offset:2048
	s_nop 0
	global_load_dwordx4 v[140:143], v[140:141], off offset:3072
	s_waitcnt vmcnt(7)
	v_mfma_f32_32x32x16_bf16 v[48:63], v[156:159], v[80:83], v[48:63]
	v_exp_f32_e32 v88, v88
	v_exp_f32_e32 v89, v89
	v_exp_f32_e32 v90, v90
	v_exp_f32_e32 v91, v91
	s_waitcnt vmcnt(6)
	v_mfma_f32_32x32x16_bf16 v[32:47], v[152:155], v[80:83], v[32:47]
	v_exp_f32_e32 v92, v92
	v_exp_f32_e32 v93, v93
	v_exp_f32_e32 v94, v94
	v_exp_f32_e32 v95, v95
	v_exp_f32_e32 v64, v64
	v_exp_f32_e32 v65, v65
	v_exp_f32_e32 v66, v66
	v_exp_f32_e32 v67, v67
	v_add_f32_e64 v218, v88, v218
	v_add_f32_e64 v219, v89, v219
	v_add_f32_e64 v218, v90, v218
	v_add_f32_e64 v219, v91, v219
	v_cvt_pk_bf16_f32 v84, v88, v89
	v_cvt_pk_bf16_f32 v85, v90, v91
	v_cvt_pk_bf16_f32 v86, v92, v93
	v_cvt_pk_bf16_f32 v87, v94, v95
	v_cndmask_b32_e32 v84, 0, v84, vcc
	v_cndmask_b32_e32 v85, 0, v85, vcc
	v_cndmask_b32_e32 v86, 0, v86, vcc
	v_cndmask_b32_e32 v87, 0, v87, vcc
	v_pk_add_f32 v[218:219], v[92:93], v[218:219]
	v_exp_f32_e32 v68, v68
	v_exp_f32_e32 v69, v69
	s_waitcnt vmcnt(5)
	v_mfma_f32_32x32x16_bf16 v[48:63], v[148:151], v[84:87], v[48:63]
	v_exp_f32_e32 v70, v70
	v_exp_f32_e32 v71, v71
	v_pk_add_f32 v[218:219], v[94:95], v[218:219]
	v_add_f32_e64 v80, v64, 0
	v_add_f32_e64 v81, v65, 0
	s_waitcnt vmcnt(4)
	v_mfma_f32_32x32x16_bf16 v[32:47], v[144:147], v[84:87], v[32:47]
	v_pk_add_f32 v[80:81], v[66:67], v[80:81]
	v_add_f32_e32 v218, v218, v219
	v_cvt_pk_bf16_f32 v64, v64, v65
	v_cvt_pk_bf16_f32 v65, v66, v67
	v_cvt_pk_bf16_f32 v66, v68, v69
	v_cvt_pk_bf16_f32 v67, v70, v71
	v_pk_add_f32 v[80:81], v[68:69], v[80:81]
	v_cndmask_b32_e32 v216, 0, v218, vcc
	v_cndmask_b32_e32 v64, 0, v64, vcc
	v_cndmask_b32_e32 v65, 0, v65, vcc
	v_cndmask_b32_e32 v66, 0, v66, vcc
	v_cndmask_b32_e32 v67, 0, v67, vcc
	v_add_f32_e32 v215, v215, v216
	v_add_f32_e64 v68, v70, v80
	v_add_f32_e64 v69, v71, v81
	v_mfma_f32_32x32x16_bf16 v[16:31], v[156:159], v[64:67], v[16:31]
	v_exp_f32_e32 v72, v72
	v_exp_f32_e32 v73, v73
	v_exp_f32_e32 v74, v74
	v_exp_f32_e32 v75, v75
	v_mfma_f32_32x32x16_bf16 v[0:15], v[152:155], v[64:67], v[0:15]
	v_exp_f32_e32 v76, v76
	v_exp_f32_e32 v77, v77
	v_exp_f32_e32 v70, v78
	v_exp_f32_e32 v71, v79
	v_pk_add_f32 v[68:69], v[72:73], v[68:69]
	v_add_f32_e64 v68, v74, v68
	v_add_f32_e64 v69, v75, v69
	v_pk_add_f32 v[68:69], v[76:77], v[68:69]
	v_cvt_pk_bf16_f32 v72, v72, v73
	v_cvt_pk_bf16_f32 v65, v74, v75
	v_cvt_pk_bf16_f32 v66, v76, v77
	v_cvt_pk_bf16_f32 v67, v70, v71
	v_pk_add_f32 v[68:69], v[70:71], v[68:69]
	v_cndmask_b32_e32 v64, 0, v72, vcc
	v_cndmask_b32_e32 v65, 0, v65, vcc
	v_cndmask_b32_e32 v66, 0, v66, vcc
	v_cndmask_b32_e32 v67, 0, v67, vcc
	v_add_f32_e32 v68, v68, v69
	s_nop 0
	v_mfma_f32_32x32x16_bf16 v[16:31], v[148:151], v[64:67], v[16:31]
	v_cndmask_b32_e32 v68, 0, v68, vcc
	v_mfma_f32_32x32x16_bf16 v[0:15], v[144:147], v[64:67], v[0:15]
	v_add_f32_e32 v214, v214, v68
	s_mov_b32 s62, s20
	s_mov_b32 s21, s3
	s_branch .LBB0_809
